# v62 but attention outputs stored write-back (plain) with buffer_wbl2 kept at seam 5
# baseline (speedup 1.0000x reference)
.LBB0_650:
	v_add_f32_e32 v0, v64, v65
	v_add_f32_e32 v0, v66, v0
	v_add_f32_e32 v0, v67, v0
	v_add_f32_e32 v0, v68, v0
	v_add_f32_e32 v0, v69, v0
	v_add_f32_e32 v0, v70, v0
	v_add_f32_e32 v0, v71, v0
	v_add_f32_e32 v0, v72, v0
	v_add_f32_e32 v0, v73, v0
	v_add_f32_e32 v0, v74, v0
	v_add_f32_e32 v0, v75, v0
	v_add_f32_e32 v0, v76, v0
	v_add_f32_e32 v0, v77, v0
	v_add_f32_e32 v0, v78, v0
	v_add_f32_e32 v0, v79, v0
	v_add_f32_e32 v0, v48, v0
	v_add_f32_e32 v0, v49, v0
	v_add_f32_e32 v0, v50, v0
	v_add_f32_e32 v0, v51, v0
	v_add_f32_e32 v0, v52, v0
	v_add_f32_e32 v0, v53, v0
	v_add_f32_e32 v0, v54, v0
	v_add_f32_e32 v0, v55, v0
	v_add_f32_e32 v0, v56, v0
	v_add_f32_e32 v0, v57, v0
	v_add_f32_e32 v0, v58, v0
	v_add_f32_e32 v0, v59, v0
	v_add_f32_e32 v0, v60, v0
	s_lshl_b64 s[16:17], s[10:11], 10
	v_add_f32_e32 v0, v61, v0
	s_cmp_lg_u32 0, -1
	v_add_f32_e32 v0, v62, v0
	s_cselect_b32 s10, 0, 0
	v_add_f32_e32 v0, v63, v0
	s_addk_i32 s10, 0x6000
	v_add_f32_e32 v0, v93, v0
	v_cvt_pk_bf16_f32 v48, v48, v49
	v_add3_u32 v95, v213, s10, v209
	v_cvt_pk_bf16_f32 v64, v64, v65
	v_cvt_pk_bf16_f32 v65, v66, v67
	v_cvt_pk_bf16_f32 v66, v68, v69
	v_cvt_pk_bf16_f32 v67, v70, v71
	v_cvt_pk_bf16_f32 v68, v72, v73
	v_cvt_pk_bf16_f32 v69, v74, v75
	v_cvt_pk_bf16_f32 v70, v76, v77
	v_cvt_pk_bf16_f32 v71, v78, v79
	v_cvt_pk_bf16_f32 v49, v50, v51
	v_cvt_pk_bf16_f32 v50, v52, v53
	v_cvt_pk_bf16_f32 v51, v54, v55
	v_cvt_pk_bf16_f32 v52, v56, v57
	v_cvt_pk_bf16_f32 v53, v58, v59
	v_cvt_pk_bf16_f32 v54, v60, v61
	v_cvt_pk_bf16_f32 v55, v62, v63
	v_add3_u32 v93, v95, v212, s87
	ds_read_b64_tr_b16 v[56:57],v93 offset:0
	ds_read_b64_tr_b16 v[58:59],v93 offset:512
	ds_read_b64_tr_b16 v[60:61],v93 offset:1024
	ds_read_b64_tr_b16 v[62:63],v93 offset:1536
	ds_read_b64_tr_b16 v[72:73],v93 offset:2048
	ds_read_b64_tr_b16 v[74:75],v93 offset:2560
	ds_read_b64_tr_b16 v[76:77],v93 offset:3072
	ds_read_b64_tr_b16 v[78:79],v93 offset:3584
	s_waitcnt lgkmcnt(0)
	s_nop 0
	v_mfma_f32_32x32x16_bf16 v[32:47], v[64:67], v[56:59], v[32:47]
	ds_read_b64_tr_b16 v[56:57],v93 offset:4096
	ds_read_b64_tr_b16 v[58:59],v93 offset:4608
	v_mfma_f32_32x32x16_bf16 v[32:47], v[68:71], v[60:63], v[32:47]
	ds_read_b64_tr_b16 v[60:61],v93 offset:5120
	ds_read_b64_tr_b16 v[62:63],v93 offset:5632
	v_mfma_f32_32x32x16_bf16 v[32:47], v[48:51], v[72:75], v[32:47]
	ds_read_b64_tr_b16 v[72:73],v93 offset:6144
	ds_read_b64_tr_b16 v[74:75],v93 offset:6656
	ds_read_b64_tr_b16 v[96:97],v93 offset:7168
	ds_read_b64_tr_b16 v[98:99],v93 offset:7680
	s_waitcnt lgkmcnt(0)
	v_mfma_f32_32x32x16_bf16 v[32:47], v[52:55], v[76:79], v[32:47]
	v_mfma_f32_32x32x16_bf16 v[16:31], v[64:67], v[56:59], v[16:31]
	v_cmp_gt_u32_e64 s[10:11], 32, v206
	v_mfma_f32_32x32x16_bf16 v[16:31], v[68:71], v[60:63], v[16:31]
	v_mfma_f32_32x32x16_bf16 v[16:31], v[48:51], v[72:75], v[16:31]
	v_mov_b32_e32 v48, v0
	s_nop 1
	v_permlane32_swap_b32_e32 v0, v48
	v_mfma_f32_32x32x16_bf16 v[16:31], v[52:55], v[96:99], v[16:31]
	s_and_saveexec_b64 s[60:61], s[10:11]
	v_add_f32_e32 v0, v0, v48
	ds_write_b32 v214, v0 offset:49280
	s_or_b64 exec, exec, s[60:61]
	s_waitcnt lgkmcnt(0)
	ds_read_b128 v[48:51], v94 offset:49280
	ds_read_b128 v[52:55], v94 offset:49312
	s_lshl_b64 s[16:17], s[16:17], 1
	s_add_u32 s16, s28, s16
	s_addc_u32 s17, s29, s17
	s_waitcnt lgkmcnt(1)
	v_rcp_f32_e32 v0, v48
	v_rcp_f32_e32 v56, v49
	s_add_u32 s12, s16, s12
	s_addc_u32 s13, s17, s13
	s_lshl_b32 s16, s78, 12
	s_add_i32 s16, s16, 0
	v_lshlrev_b32_e32 v63, 1, v207
	v_lshlrev_b32_e32 v64, 9, v208
	v_mul_f32_e32 v32, v32, v0
	v_mul_f32_e32 v0, v16, v0
	v_add3_u32 v63, s16, v63, v64
	v_cvt_pk_bf16_f32 v0, v0, s0
	v_rcp_f32_e32 v57, v50
	v_rcp_f32_e32 v58, v51
	s_waitcnt lgkmcnt(0)
	v_rcp_f32_e32 v59, v52
	ds_read_b128 v[48:51], v94 offset:49344
	v_rcp_f32_e32 v60, v53
	v_rcp_f32_e32 v61, v54
	v_rcp_f32_e32 v62, v55
	ds_read_b128 v[52:55], v94 offset:49376
	ds_write_b16 v63, v0 offset:51264
	v_mul_f32_e32 v0, v33, v56
	v_cvt_pk_bf16_f32 v0, v0, s0
	ds_write_b16 v63, v0 offset:51328
	v_mul_f32_e32 v0, v17, v56
	v_cvt_pk_bf16_f32 v0, v0, s0
	ds_write_b16 v63, v0 offset:51392
	v_mul_f32_e32 v0, v34, v57
	v_cvt_pk_bf16_f32 v0, v0, s0
	ds_write_b16 v63, v0 offset:51456
	v_mul_f32_e32 v0, v18, v57
	v_cvt_pk_bf16_f32 v0, v0, s0
	ds_write_b16 v63, v0 offset:51520
	v_mul_f32_e32 v0, v35, v58
	v_cvt_pk_bf16_f32 v0, v0, s0
	ds_write_b16 v63, v0 offset:51584
	v_mul_f32_e32 v0, v19, v58
	v_cvt_pk_bf16_f32 v0, v0, s0
	ds_write_b16 v63, v0 offset:51648
	v_mul_f32_e32 v0, v36, v59
	v_cvt_pk_bf16_f32 v0, v0, s0
	ds_write_b16 v63, v0 offset:52224
	v_mul_f32_e32 v0, v20, v59
	v_cvt_pk_bf16_f32 v0, v0, s0
	ds_write_b16 v63, v0 offset:52288
	v_mul_f32_e32 v0, v37, v60
	v_cvt_pk_bf16_f32 v0, v0, s0
	ds_write_b16 v63, v0 offset:52352
	v_mul_f32_e32 v0, v21, v60
	v_cvt_pk_bf16_f32 v0, v0, s0
	ds_write_b16 v63, v0 offset:52416
	v_mul_f32_e32 v0, v38, v61
	v_cvt_pk_bf16_f32 v0, v0, s0
	ds_write_b16 v63, v0 offset:52480
	v_mul_f32_e32 v0, v22, v61
	v_cvt_pk_bf16_f32 v0, v0, s0
	s_waitcnt lgkmcnt(13)
	v_rcp_f32_e32 v48, v48
	ds_write_b16 v63, v0 offset:52544
	v_mul_f32_e32 v0, v39, v62
	v_cvt_pk_bf16_f32 v0, v0, s0
	ds_write_b16 v63, v0 offset:52608
	v_mul_f32_e32 v0, v23, v62
	v_cvt_pk_bf16_f32 v0, v0, s0
	v_rcp_f32_e32 v49, v49
	ds_write_b16 v63, v0 offset:52672
	v_mul_f32_e32 v0, v40, v48
	v_cvt_pk_bf16_f32 v0, v0, s0
	ds_write_b16 v63, v0 offset:53248
	v_mul_f32_e32 v0, v24, v48
	v_cvt_pk_bf16_f32 v0, v0, s0
	v_rcp_f32_e32 v50, v50
	ds_write_b16 v63, v0 offset:53312
	v_mul_f32_e32 v0, v41, v49
	v_cvt_pk_bf16_f32 v0, v0, s0
	ds_write_b16 v63, v0 offset:53376
	v_mul_f32_e32 v0, v25, v49
	v_cvt_pk_bf16_f32 v0, v0, s0
	v_rcp_f32_e32 v51, v51
	ds_write_b16 v63, v0 offset:53440
	v_mul_f32_e32 v0, v42, v50
	v_cvt_pk_bf16_f32 v0, v0, s0
	ds_write_b16 v63, v0 offset:53504
	v_mul_f32_e32 v0, v26, v50
	v_cvt_pk_bf16_f32 v0, v0, s0
	s_waitcnt lgkmcnt(14)
	v_rcp_f32_e32 v52, v52
	ds_write_b16 v63, v0 offset:53568
	v_mul_f32_e32 v0, v43, v51
	v_cvt_pk_bf16_f32 v0, v0, s0
	ds_write_b16 v63, v0 offset:53632
	v_mul_f32_e32 v0, v27, v51
	v_cvt_pk_bf16_f32 v0, v0, s0
	v_rcp_f32_e32 v53, v53
	ds_write_b16 v63, v0 offset:53696
	v_mul_f32_e32 v0, v44, v52
	v_cvt_pk_bf16_f32 v0, v0, s0
	ds_write_b16 v63, v0 offset:54272
	v_mul_f32_e32 v0, v28, v52
	v_cvt_pk_bf16_f32 v0, v0, s0
	v_rcp_f32_e32 v54, v54
	ds_write_b16 v63, v0 offset:54336
	v_mul_f32_e32 v0, v45, v53
	v_cvt_pk_bf16_f32 v0, v0, s0
	ds_write_b16 v63, v0 offset:54400
	v_mul_f32_e32 v0, v29, v53
	v_cvt_pk_bf16_f32 v0, v0, s0
	v_rcp_f32_e32 v55, v55
	ds_write_b16 v63, v0 offset:54464
	v_mul_f32_e32 v0, v46, v54
	v_cvt_pk_bf16_f32 v0, v0, s0
	ds_write_b16 v63, v0 offset:54528
	v_mul_f32_e32 v0, v30, v54
	v_cvt_pk_bf16_f32 v0, v0, s0
	ds_write_b16 v63, v0 offset:54592
	v_mul_f32_e32 v0, v47, v55
	v_cvt_pk_bf16_f32 v0, v0, s0
	ds_write_b16 v63, v0 offset:54656
	v_mul_f32_e32 v0, v31, v55
	v_cvt_pk_bf16_f32 v32, v32, s0
	v_cvt_pk_bf16_f32 v0, v0, s0
	ds_write_b16 v63, v32 offset:51200
	ds_write_b16 v63, v0 offset:54720
	v_lshlrev_b32_e32 v0, 7, v14
	v_lshlrev_b32_e32 v14, 1, v90
	s_waitcnt lgkmcnt(0)
	v_add3_u32 v0, s16, v0, v14
	ds_read_b128 v[16:19], v0 offset:51200
	ds_read_b128 v[20:23], v0 offset:52224
	s_waitcnt vmcnt(3)
	v_lshlrev_b32_e32 v28, 16, v80
	v_and_b32_e32 v29, 0xffff0000, v80
	v_lshl_add_u64 v[24:25], v[88:89], 1, s[12:13]
	s_waitcnt lgkmcnt(1)
	v_lshlrev_b32_e32 v26, 16, v16
	v_and_b32_e32 v27, 0xffff0000, v16
	v_pk_mul_f32 v[26:27], v[28:29], v[26:27]
	v_lshlrev_b32_e32 v28, 16, v81
	v_cvt_pk_bf16_f32 v16, v26, v27
	v_lshlrev_b32_e32 v26, 16, v17
	v_and_b32_e32 v27, 0xffff0000, v17
	v_and_b32_e32 v29, 0xffff0000, v81
	v_pk_mul_f32 v[26:27], v[28:29], v[26:27]
	v_lshlrev_b32_e32 v28, 16, v82
	v_cvt_pk_bf16_f32 v17, v26, v27
	v_lshlrev_b32_e32 v26, 16, v18
	v_and_b32_e32 v27, 0xffff0000, v18
	v_and_b32_e32 v29, 0xffff0000, v82
	v_pk_mul_f32 v[26:27], v[28:29], v[26:27]
	v_lshlrev_b32_e32 v28, 16, v83
	v_cvt_pk_bf16_f32 v18, v26, v27
	v_lshlrev_b32_e32 v26, 16, v19
	v_and_b32_e32 v27, 0xffff0000, v19
	v_and_b32_e32 v29, 0xffff0000, v83
	v_pk_mul_f32 v[26:27], v[28:29], v[26:27]
	s_nop 0
	v_cvt_pk_bf16_f32 v19, v26, v27
	global_store_dwordx4 v[24:25], v[16:19], off
	s_waitcnt lgkmcnt(0)
	s_nop 0
	v_lshlrev_b32_e32 v16, 16, v20
	v_and_b32_e32 v17, 0xffff0000, v20
	s_waitcnt vmcnt(3)
	v_lshlrev_b32_e32 v18, 16, v10
	v_and_b32_e32 v19, 0xffff0000, v10
	v_pk_mul_f32 v[16:17], v[18:19], v[16:17]
	v_lshlrev_b32_e32 v18, 16, v11
	v_cvt_pk_bf16_f32 v10, v16, v17
	v_lshlrev_b32_e32 v16, 16, v21
	v_and_b32_e32 v17, 0xffff0000, v21
	v_and_b32_e32 v19, 0xffff0000, v11
	v_pk_mul_f32 v[16:17], v[18:19], v[16:17]
	v_lshlrev_b32_e32 v18, 16, v12
	v_cvt_pk_bf16_f32 v11, v16, v17
	v_lshlrev_b32_e32 v16, 16, v22
	v_and_b32_e32 v17, 0xffff0000, v22
	v_and_b32_e32 v19, 0xffff0000, v12
	v_pk_mul_f32 v[16:17], v[18:19], v[16:17]
	v_lshlrev_b32_e32 v18, 16, v13
	v_cvt_pk_bf16_f32 v12, v16, v17
	v_lshlrev_b32_e32 v16, 16, v23
	v_and_b32_e32 v17, 0xffff0000, v23
	v_and_b32_e32 v19, 0xffff0000, v13
	v_pk_mul_f32 v[16:17], v[18:19], v[16:17]
	v_add_co_u32_e32 v20, vcc, s68, v24
	v_cvt_pk_bf16_f32 v13, v16, v17
	ds_read_b128 v[16:19], v0 offset:53248
	v_addc_co_u32_e32 v21, vcc, 0, v25, vcc
	global_store_dwordx4 v[20:21], v[10:13], off
	ds_read_b128 v[10:13], v0 offset:54272
	s_waitcnt lgkmcnt(1)
	v_lshlrev_b32_e32 v20, 16, v16
	v_and_b32_e32 v21, 0xffff0000, v16
	s_waitcnt vmcnt(3)
	v_lshlrev_b32_e32 v22, 16, v6
	v_and_b32_e32 v23, 0xffff0000, v6
	v_pk_mul_f32 v[20:21], v[22:23], v[20:21]
	v_lshlrev_b32_e32 v16, 16, v17
	v_cvt_pk_bf16_f32 v6, v20, v21
	v_and_b32_e32 v17, 0xffff0000, v17
	v_lshlrev_b32_e32 v20, 16, v7
	v_and_b32_e32 v21, 0xffff0000, v7
	v_pk_mul_f32 v[16:17], v[20:21], v[16:17]
	v_lshlrev_b32_e32 v20, 16, v8
	v_cvt_pk_bf16_f32 v7, v16, v17
	v_lshlrev_b32_e32 v16, 16, v18
	v_and_b32_e32 v17, 0xffff0000, v18
	v_and_b32_e32 v21, 0xffff0000, v8
	v_pk_mul_f32 v[16:17], v[20:21], v[16:17]
	v_lshlrev_b32_e32 v18, 16, v9
	v_cvt_pk_bf16_f32 v8, v16, v17
	v_lshlrev_b32_e32 v16, 16, v19
	v_and_b32_e32 v17, 0xffff0000, v19
	v_and_b32_e32 v19, 0xffff0000, v9
	v_pk_mul_f32 v[16:17], v[18:19], v[16:17]
	s_nop 0
	v_cvt_pk_bf16_f32 v9, v16, v17
	v_add_co_u32_e32 v16, vcc, s70, v24
	s_nop 1
	v_addc_co_u32_e32 v17, vcc, 0, v25, vcc
	global_store_dwordx4 v[16:17], v[6:9], off
	s_waitcnt lgkmcnt(0)
	s_nop 0
	v_lshlrev_b32_e32 v6, 16, v10
	v_and_b32_e32 v7, 0xffff0000, v10
	s_waitcnt vmcnt(3)
	v_lshlrev_b32_e32 v8, 16, v2
	v_and_b32_e32 v9, 0xffff0000, v2
	v_pk_mul_f32 v[6:7], v[8:9], v[6:7]
	v_lshlrev_b32_e32 v8, 16, v3
	v_cvt_pk_bf16_f32 v2, v6, v7
	v_lshlrev_b32_e32 v6, 16, v11
	v_and_b32_e32 v7, 0xffff0000, v11
	v_and_b32_e32 v9, 0xffff0000, v3
	v_pk_mul_f32 v[6:7], v[8:9], v[6:7]
	v_lshlrev_b32_e32 v8, 16, v4
	v_cvt_pk_bf16_f32 v3, v6, v7
	v_lshlrev_b32_e32 v6, 16, v12
	v_and_b32_e32 v7, 0xffff0000, v12
	v_and_b32_e32 v9, 0xffff0000, v4
	v_pk_mul_f32 v[6:7], v[8:9], v[6:7]
	v_lshlrev_b32_e32 v8, 16, v5
	v_cvt_pk_bf16_f32 v4, v6, v7
	v_lshlrev_b32_e32 v6, 16, v13
	v_and_b32_e32 v7, 0xffff0000, v13
	v_and_b32_e32 v9, 0xffff0000, v5
	v_pk_mul_f32 v[6:7], v[8:9], v[6:7]
	s_nop 0
	v_cvt_pk_bf16_f32 v5, v6, v7
	v_add_co_u32_e32 v6, vcc, 0xc000, v24
	s_nop 1
	v_addc_co_u32_e32 v7, vcc, 0, v25, vcc
	s_and_b64 vcc, exec, s[0:1]
	global_store_dwordx4 v[6:7], v[2:5], off
	s_cbranch_vccnz .LBB0_544
	s_xor_b32 s20, s77, 1
	s_cmpk_gt_i32 s14, 0x3ff
	s_mov_b64 s[0:1], -1
	s_cbranch_scc1 .LBB0_661
	v_add_f32_e32 v0, v87, v15
	v_add_f32_e32 v2, v0, v92
	v_add_f32_e32 v6, v2, v91
	v_lshlrev_b32_e32 v5, 2, v206
	v_mov_b32_e32 v3, v6
	s_nop 1
	v_add_f32_dpp v3, v3, v3 row_shr:1 row_mask:0xf bank_mask:0xf
	s_nop 1
	v_add_f32_dpp v3, v3, v3 row_shr:2 row_mask:0xf bank_mask:0xf
	s_nop 1
	v_add_f32_dpp v3, v3, v3 row_shr:4 row_mask:0xf bank_mask:0xf
	s_nop 1
	v_add_f32_dpp v3, v3, v3 row_shr:8 row_mask:0xf bank_mask:0xf
	s_nop 1
	v_add_f32_dpp v3, v3, v3 row_bcast:15 row_mask:0xa bank_mask:0xf
	s_nop 1
	v_add_f32_dpp v3, v3, v3 row_bcast:31 row_mask:0xc bank_mask:0xf
	s_nop 0
	v_sub_f32_e32 v8, v3, v6
	v_xad_u32 v4, v5, -1, s15
	v_add_f32_e32 v5, v87, v8
	v_add_f32_e32 v3, v0, v8
	v_add_f32_e32 v0, v6, v8
	v_sub_f32_e32 v6, v5, v87
	v_cmp_ge_f32_e64 s[0:1], v6, -v197
	v_sub_f32_e32 v6, v3, v15
	v_add_f32_e32 v2, v2, v8
	v_cmp_lt_i32_e64 s[10:11], 0, v4
	v_cmp_ge_f32_e64 s[16:17], v6, -v197
	v_cmp_lt_i32_e64 s[12:13], -1, v4
	s_and_b64 s[16:17], s[10:11], s[16:17]
	s_bcnt1_i32_b64 s60, s[16:17]
	v_sub_f32_e32 v8, v2, v92
	s_and_b64 vcc, s[12:13], s[0:1]
	s_bcnt1_i32_b64 s61, vcc
	s_add_i32 s60, s60, s61
	v_cmp_lt_i32_e64 s[0:1], 1, v4
	v_cmp_ge_f32_e64 s[16:17], v8, -v197
	s_and_b64 s[16:17], s[0:1], s[16:17]
	s_bcnt1_i32_b64 s61, s[16:17]
	s_add_i32 s60, s60, s61
	v_sub_f32_e32 v9, v0, v91
	v_cmp_lt_i32_e32 vcc, 2, v4
	v_cmp_ge_f32_e64 s[16:17], v9, -v197
	s_and_b64 s[16:17], vcc, s[16:17]
	s_bcnt1_i32_b64 s61, s[16:17]
	s_add_i32 s60, s60, s61
	s_lshl_b32 s16, s20, 10
	s_add_i32 s56, s16, 0
	s_add_i32 s56, s56, 0x24800
	s_and_saveexec_b64 s[16:17], s[12:13]
	s_cbranch_execnz .LBB0_664
	s_or_b64 exec, exec, s[16:17]
	v_lshlrev_b32_e32 v4, 2, v4
	s_and_saveexec_b64 s[12:13], s[10:11]
	s_cbranch_execnz .LBB0_665

.LBB0_706:
	s_or_b64 exec, exec, s[10:11]
	v_cvt_f32_u32_e32 v4, v2
	s_waitcnt vmcnt(0)
	v_readfirstlane_b32 s8, v3
	v_sub_u32_e32 v3, 0, v2
	v_rcp_iflag_f32_e32 v4, v4
	v_add_u32_e32 v5, s8, v1
	v_mul_f32_e32 v4, 0x4f7ffffe, v4
	v_cvt_u32_f32_e32 v4, v4
	v_mul_lo_u32 v1, v3, v4
	v_mul_hi_u32 v1, v4, v1
	v_add_u32_e32 v1, v4, v1
	v_mul_hi_u32 v1, v5, v1
	v_mul_lo_u32 v3, v1, v2
	v_sub_u32_e32 v3, v5, v3
	v_add_u32_e32 v4, 1, v1
	v_cmp_ge_u32_e32 vcc, v3, v2
	s_nop 1
	v_cndmask_b32_e32 v1, v1, v4, vcc
	v_sub_u32_e32 v4, v3, v2
	v_cndmask_b32_e32 v3, v3, v4, vcc
	v_add_u32_e32 v4, 1, v1
	v_cmp_ge_u32_e32 vcc, v3, v2
	v_add_u32_e32 v3, 1, v5
	s_nop 0
	v_cndmask_b32_e32 v1, v1, v4, vcc
	v_mul_lo_u32 v4, v2, v1
	v_add_u32_e32 v2, v4, v2
	v_cmp_ne_u32_e32 vcc, v3, v2
	s_cbranch_vccnz .Lmy_ft5_nl
	buffer_wbl2 sc1
	s_waitcnt vmcnt(0) lgkmcnt(0)
	v_mov_b32_e32 v2, 0x3000
	v_mov_b32_e32 v3, 1
	global_atomic_add v2, v3, s[52:53] offset:1024
